# hbkeep10: 10 of 16 bf16 h blocks kept in VGPRs from P3 epilogue to P4 epilogue (two more blocks, second chunk)
# speedup vs baseline: 1.0079x; 1.0015x over previous
; __device__ __forceinline__ unsigned cvtpk(float lo, float hi) { f32x2 v = {lo, hi}; bf16x2_t b = __builtin_convertvector(v, bf16x2_t); return __builtin_bit_cast(unsigned, b); }
;     __device__ __forceinline__ void operator()(const Acc& acc, const Unit& u, int wr, int wc, int fr, int fq) const {
;     ...
;             for (int m = 0; m < 4; ++m) { const size_t off = (size_t)(u.pm * 256 + ai * 128 + wr * 64 + m * 16 + fr) * DM + colbase;
; #pragma unroll
;                 for (int bj = 0; bj < 2; ++bj) { xv[m][bj][0] = __builtin_nontemporal_load((const f32x4*)(x + off + 32 * bj)); xv[m][bj][1] = __builtin_nontemporal_load((const f32x4*)(x + off + 32 * bj + 4)); } }
; #pragma unroll
;             for (int m = 0; m < 4; ++m) {
;                 const int row = u.pm * 256 + ai * 128 + wr * 64 + m * 16 + fr;
;                 float ss = 0.f;
; #pragma unroll
;                 for (int bj = 0; bj < 2; ++bj) {
;                     const size_t off = (size_t)row * DM + colbase + 32 * bj;
;                     const f32x4 h0 = xv[m][bj][0] + acc[ai][bj][m][0], h1 = xv[m][bj][1] + acc[ai][bj][m][1];
;                     u32x4 w; w.x = cvtpk(h0.x, h0.y); w.y = cvtpk(h0.z, h0.w); w.z = cvtpk(h1.x, h1.y); w.w = cvtpk(h1.z, h1.w);
;                     *(u32x4*)(HB + off) = w;
;                     ss += (h0.x * h0.x + h0.y * h0.y) + (h0.z * h0.z + h0.w * h0.w) + (h1.x * h1.x + h1.y * h1.y) + (h1.z * h1.z + h1.w * h1.w);
;                 }
;                 ss = quad_sum(ss);
;                 if (fq == 0) atomicAdd(rowss + row, ss);
.LBB0_733:
	s_or_b64 exec, exec, s[20:21]
	v_add_u32_e32 v136, 0x80, v192
	v_ashrrev_i32_e32 v137, 31, v136
	v_lshlrev_b64 v[64:65], 13, v[136:137]
	v_lshl_add_u64 v[64:65], v[190:191], 0, v[64:65]
	flat_load_dwordx4 v[120:123], v[64:65] nt
	flat_load_dwordx4 v[124:127], v[64:65] offset:16 nt
	flat_load_dwordx4 v[128:131], v[64:65] offset:128 nt
	flat_load_dwordx4 v[132:135], v[64:65] offset:144 nt
	v_add_u32_e32 v118, 0x90, v192
	v_add_u32_e32 v116, 0xa0, v192
	v_add_u32_e32 v114, 0xb0, v192
	v_ashrrev_i32_e32 v119, 31, v118
	v_ashrrev_i32_e32 v117, 31, v116
	v_ashrrev_i32_e32 v115, 31, v114
	v_lshlrev_b64 v[64:65], 13, v[118:119]
	v_lshlrev_b64 v[66:67], 13, v[116:117]
	v_lshlrev_b64 v[68:69], 13, v[114:115]
	v_lshl_add_u64 v[64:65], v[190:191], 0, v[64:65]
	v_lshl_add_u64 v[66:67], v[190:191], 0, v[66:67]
	v_lshl_add_u64 v[138:139], v[190:191], 0, v[68:69]
	flat_load_dwordx4 v[108:111], v[64:65] nt
	flat_load_dwordx4 v[104:107], v[64:65] offset:16 nt
	flat_load_dwordx4 v[100:103], v[64:65] offset:128 nt
	flat_load_dwordx4 v[96:99], v[64:65] offset:144 nt
	flat_load_dwordx4 v[92:95], v[66:67] nt
	flat_load_dwordx4 v[88:91], v[66:67] offset:16 nt
	flat_load_dwordx4 v[84:87], v[66:67] offset:128 nt
	flat_load_dwordx4 v[80:83], v[66:67] offset:144 nt
	flat_load_dwordx4 v[76:79], v[138:139] nt
	flat_load_dwordx4 v[72:75], v[138:139] offset:16 nt
	flat_load_dwordx4 v[68:71], v[138:139] offset:128 nt
	s_nop 0
	flat_load_dwordx4 v[64:67], v[138:139] offset:144 nt
	v_lshlrev_b64 v[136:137], 12, v[136:137]
	v_lshl_add_u64 v[136:137], s[10:11], 0, v[136:137]
	v_lshl_add_u64 v[136:137], v[188:189], 1, v[136:137]
	s_waitcnt vmcnt(0) lgkmcnt(0)
	v_pk_add_f32 v[62:63], v[62:63], v[122:123]
	v_pk_add_f32 v[60:61], v[60:61], v[120:121]
	v_pk_add_f32 v[54:55], v[54:55], v[130:131]
	v_pk_add_f32 v[120:121], v[52:53], v[128:129]
	v_pk_add_f32 v[56:57], v[56:57], v[124:125]
	v_pk_add_f32 v[124:125], v[48:49], v[132:133]
	v_cvt_pk_bf16_f32 v48, v60, v61
	v_cvt_pk_bf16_f32 v49, v62, v63
	v_mul_f32_e32 v61, v61, v61
	v_mul_f32_e32 v63, v63, v63
	v_cvt_pk_bf16_f32 v52, v120, v121
	v_cvt_pk_bf16_f32 v53, v54, v55
	v_mul_f32_e32 v121, v121, v121
	v_mul_f32_e32 v55, v55, v55
	v_pk_add_f32 v[58:59], v[58:59], v[126:127]
	v_pk_add_f32 v[122:123], v[50:51], v[134:135]
	v_cvt_pk_bf16_f32 v50, v56, v57
	v_mul_f32_e32 v57, v57, v57
	v_mul_f32_e32 v126, v125, v125
	v_fmac_f32_e32 v61, v60, v60
	v_fmac_f32_e32 v63, v62, v62
	v_fmac_f32_e32 v121, v120, v120
	v_fmac_f32_e32 v55, v54, v54
	v_cvt_pk_bf16_f32 v51, v58, v59
	v_mul_f32_e32 v59, v59, v59
	v_mul_f32_e32 v127, v123, v123
	v_fmac_f32_e32 v57, v56, v56
	v_fmac_f32_e32 v126, v124, v124
	v_add_f32_e32 v54, v61, v63
	v_add_f32_e32 v55, v121, v55
	v_fmac_f32_e32 v59, v58, v58
	v_fmac_f32_e32 v127, v122, v122
	v_add_f32_e32 v54, v54, v57
	v_add_f32_e32 v55, v55, v126
	v_add_f32_e32 v54, v59, v54
	v_add_f32_e32 v55, v127, v55
	v_add_f32_e32 v56, v54, v55
	ds_swizzle_b32 v57, v56 offset:swizzle(SWAP,16)
	v_cvt_pk_bf16_f32 v54, v124, v125
	v_cvt_pk_bf16_f32 v55, v122, v123
	v_mov_b64_e32 v[248:249], v[48:49]
	v_mov_b64_e32 v[252:253], v[50:51]
	flat_store_dwordx4 v[136:137], v[48:51]
	v_mov_b64_e32 v[218:219], v[52:53]
	v_mov_b64_e32 v[220:221], v[54:55]
	flat_store_dwordx4 v[136:137], v[52:55] offset:64
	s_waitcnt lgkmcnt(0)
	v_add_f32_e32 v48, v56, v57
	v_mov_b32_e32 v49, v48
	s_nop 1
	v_permlane32_swap_b32_e32 v48, v49
	s_and_saveexec_b64 s[20:21], vcc
	s_cbranch_execz .LBB0_735
	v_add_f32_e32 v48, v48, v49
	flat_atomic_add_f32 v[112:113], v48 offset:512

;     __device__ __forceinline__ void operator()(const Acc& acc, const Unit& u, int wr, int wc, int fr, int fq) const {
;         asm volatile("" : "+v"(fr), "+v"(fq));
;         const int colbase = u.pn * 256 + wc * 64 + 8 * fq;
; #pragma unroll
;         for (int ai = 0; ai < 2; ++ai) {
;             f32x4 hv[4][2][2]; u32x4 pw[4][2]; float rsv[4];
; #pragma unroll
;             for (int m = 0; m < 4; ++m) { const int row = u.pm * 256 + ai * 128 + wr * 64 + m * 16 + fr; const size_t off = (size_t)row * DM + colbase;
;                 rsv[m] = rowss[row];
; #pragma unroll
;                 for (int bj = 0; bj < 2; ++bj) { const u32x4 hw = __builtin_nontemporal_load((const u32x4*)(hin + off + 32 * bj));
;                     hv[m][bj][0] = (f32x4){bflo(hw.x), bfhi(hw.x), bflo(hw.y), bfhi(hw.y)}; hv[m][bj][1] = (f32x4){bflo(hw.z), bfhi(hw.z), bflo(hw.w), bfhi(hw.w)};
;                     pw[m][bj] = __builtin_nontemporal_load((const u32x4*)(PP + off + 32 * bj)); } }
; #pragma unroll
;             for (int m = 0; m < 4; ++m) {
;                 const int row = u.pm * 256 + ai * 128 + wr * 64 + m * 16 + fr;
;                 const float rs = rsqrtf(rsv[m] * (1.0f / DM) + EPS) * -1.4426950408889634f;
; #pragma unroll
;                 for (int bj = 0; bj < 2; ++bj) {
;                     const size_t off = (size_t)row * DM + colbase + 32 * bj;
;                     f32x4 h0 = hv[m][bj][0], h1 = hv[m][bj][1];
;                     const u32x4 p4 = pw[m][bj];
;                     const f32x4 a0 = acc[ai][bj][m][0], a1 = acc[ai][bj][m][1];
;                     h0.x += bflo(p4.x) * __builtin_amdgcn_rcpf(1.0f + __builtin_amdgcn_exp2f(a0.x * rs));
;                     h0.y += bfhi(p4.x) * __builtin_amdgcn_rcpf(1.0f + __builtin_amdgcn_exp2f(a0.y * rs));
;                     h0.z += bflo(p4.y) * __builtin_amdgcn_rcpf(1.0f + __builtin_amdgcn_exp2f(a0.z * rs));
;                     h0.w += bfhi(p4.y) * __builtin_amdgcn_rcpf(1.0f + __builtin_amdgcn_exp2f(a0.w * rs));
;                     h1.x += bflo(p4.z) * __builtin_amdgcn_rcpf(1.0f + __builtin_amdgcn_exp2f(a1.x * rs));
;                     h1.y += bfhi(p4.z) * __builtin_amdgcn_rcpf(1.0f + __builtin_amdgcn_exp2f(a1.y * rs));
;                     h1.z += bflo(p4.w) * __builtin_amdgcn_rcpf(1.0f + __builtin_amdgcn_exp2f(a1.z * rs));
.LBB0_814:
	v_mov_b64_e32 v[206:207], v[224:225]
	v_mov_b64_e32 v[208:209], v[226:227]
	v_mov_b64_e32 v[172:173], v[228:229]
	v_mov_b64_e32 v[174:175], v[230:231]
	v_mov_b64_e32 v[164:165], v[232:233]
	v_mov_b64_e32 v[166:167], v[234:235]
	v_mov_b64_e32 v[156:157], v[236:237]
	v_mov_b64_e32 v[158:159], v[238:239]
	v_mov_b64_e32 v[148:149], v[240:241]
	v_mov_b64_e32 v[150:151], v[242:243]
	v_mov_b64_e32 v[140:141], v[210:211]
	v_mov_b64_e32 v[142:143], v[212:213]
	v_mov_b64_e32 v[236:237], v[218:219]
	v_mov_b64_e32 v[238:239], v[220:221]
	v_mov_b32_e32 v128, v200
	s_lshl_b32 s11, s42, 8
	v_and_b32_e32 v129, 15, v128
	v_bfe_u32 v128, v128, 4, 2
	s_or_b32 s11, s11, s86
	s_nop 0
	v_lshl_add_u32 v188, v128, 3, s11
	s_lshl_b32 s11, s41, 8
	s_add_i32 s11, s11, s79
	v_add_u32_e32 v190, s11, v129
	v_ashrrev_i32_e32 v191, 31, v190
	v_lshl_add_u64 v[192:193], v[190:191], 2, s[80:81]
	flat_load_dword v226, v[192:193]
	v_ashrrev_i32_e32 v189, 31, v188
	v_lshlrev_b64 v[128:129], 11, v[190:191]
	v_lshl_add_u64 v[222:223], v[128:129], 0, v[188:189]
	v_lshlrev_b64 v[128:129], 1, v[222:223]
	v_lshl_add_u64 v[130:131], s[6:7], 0, v[128:129]
	v_lshl_add_u64 v[128:129], s[8:9], 0, v[128:129]
	flat_load_dwordx4 v[210:213], v[128:129] nt
	flat_load_dword v234, v[192:193] offset:64
	flat_load_dword v235, v[192:193] offset:128
	flat_load_dword v191, v[192:193] offset:192
	flat_load_dwordx4 v[218:221], v[128:129] offset:64 nt
	v_add_u32_e32 v132, 16, v190
	v_add_u32_e32 v134, 32, v190
	v_add_u32_e32 v136, 48, v190
	v_ashrrev_i32_e32 v133, 31, v132
	v_ashrrev_i32_e32 v135, 31, v134
	v_ashrrev_i32_e32 v137, 31, v136
	v_lshlrev_b64 v[132:133], 11, v[132:133]
	v_lshlrev_b64 v[134:135], 11, v[134:135]
	v_lshlrev_b64 v[136:137], 11, v[136:137]
	v_lshl_add_u64 v[198:199], v[132:133], 0, v[188:189]
	v_lshl_add_u64 v[196:197], v[134:135], 0, v[188:189]
	v_lshl_add_u64 v[194:195], v[136:137], 0, v[188:189]
	v_lshlrev_b64 v[132:133], 1, v[198:199]
	v_lshlrev_b64 v[134:135], 1, v[196:197]
	v_lshlrev_b64 v[136:137], 1, v[194:195]
	v_lshl_add_u64 v[128:129], s[6:7], 0, v[132:133]
	v_lshl_add_u64 v[130:131], s[8:9], 0, v[132:133]
	v_lshl_add_u64 v[132:133], s[6:7], 0, v[134:135]
	v_lshl_add_u64 v[134:135], s[8:9], 0, v[134:135]
	v_lshl_add_u64 v[138:139], s[6:7], 0, v[136:137]
	v_lshl_add_u64 v[224:225], s[8:9], 0, v[136:137]
	flat_load_dwordx4 v[168:171], v[130:131] nt
	flat_load_dwordx4 v[160:163], v[130:131] offset:64 nt
	flat_load_dwordx4 v[152:155], v[134:135] nt
	flat_load_dwordx4 v[144:147], v[134:135] offset:64 nt
	s_nop 0
	v_mov_b64_e32 v[132:133], v[244:245]
	v_mov_b64_e32 v[134:135], v[246:247]
	s_nop 0
	flat_load_dwordx4 v[136:139], v[224:225] nt
	flat_load_dwordx4 v[128:131], v[224:225] offset:64 nt
	s_waitcnt vmcnt(0) lgkmcnt(0)
	v_fmamk_f32 v224, v226, 0x3a000000, v205
	v_mul_f32_e32 v225, 0x4b800000, v224
	v_cmp_gt_f32_e32 vcc, s40, v224
	v_lshlrev_b32_e32 v228, 16, v208
	s_nop 0
	v_cndmask_b32_e32 v224, v224, v225, vcc
	v_rsq_f32_e32 v232, v224
	v_and_b32_e32 v229, 0xffff0000, v208
	v_lshlrev_b32_e32 v230, 16, v212
	v_and_b32_e32 v231, 0xffff0000, v212
	v_mul_f32_e32 v208, 0x45800000, v232
	v_cndmask_b32_e32 v208, v232, v208, vcc
	v_mul_f32_e32 v212, 0xbfb8aa3b, v208
	v_mul_f32_e32 v124, v124, v212
	v_mul_f32_e32 v125, v125, v212
	v_mul_f32_e32 v120, v120, v212
	v_mul_f32_e32 v121, v121, v212
	v_exp_f32_e32 v124, v124
	v_exp_f32_e32 v125, v125
	v_exp_f32_e32 v120, v120
	v_exp_f32_e32 v121, v121
	v_add_f32_e32 v124, 1.0, v124
	v_add_f32_e32 v125, 1.0, v125
	v_add_f32_e32 v208, 1.0, v120
	v_add_f32_e32 v233, 1.0, v121
	v_rcp_f32_e32 v120, v124
	v_rcp_f32_e32 v121, v125
	v_lshlrev_b32_e32 v224, 16, v206
	v_and_b32_e32 v225, 0xffff0000, v206
	v_lshlrev_b32_e32 v226, 16, v210
	v_and_b32_e32 v227, 0xffff0000, v210
	v_mul_f32_e32 v126, v126, v212
	v_mul_f32_e32 v127, v127, v212
	v_mul_f32_e32 v122, v122, v212
	v_exp_f32_e32 v126, v126
	v_exp_f32_e32 v127, v127
	v_pk_fma_f32 v[124:125], v[120:121], v[226:227], v[224:225]
	v_mul_f32_e32 v120, v123, v212
	v_exp_f32_e32 v122, v122
	v_exp_f32_e32 v123, v120
	v_mul_f32_e32 v116, v116, v212
	v_mul_f32_e32 v117, v117, v212
	v_exp_f32_e32 v116, v116
	v_exp_f32_e32 v117, v117
	v_mul_f32_e32 v118, v118, v212
	v_mul_f32_e32 v119, v119, v212
	v_add_f32_e32 v126, 1.0, v126
	v_add_f32_e32 v127, 1.0, v127
	v_exp_f32_e32 v118, v118
	v_exp_f32_e32 v119, v119
	v_mul_f32_e32 v112, v112, v212
	v_mul_f32_e32 v113, v113, v212
	v_rcp_f32_e32 v126, v126
	v_rcp_f32_e32 v127, v127
	v_add_f32_e32 v122, 1.0, v122
	v_add_f32_e32 v123, 1.0, v123
	v_exp_f32_e32 v112, v112
	v_exp_f32_e32 v113, v113
	v_rcp_f32_e32 v232, v208
	v_rcp_f32_e32 v233, v233
	v_rcp_f32_e32 v122, v122
	v_rcp_f32_e32 v123, v123
	v_add_f32_e32 v116, 1.0, v116
	v_add_f32_e32 v117, 1.0, v117
	v_lshlrev_b32_e32 v206, 16, v207
	v_and_b32_e32 v207, 0xffff0000, v207
	v_lshlrev_b32_e32 v210, 16, v211
	v_and_b32_e32 v211, 0xffff0000, v211
	v_rcp_f32_e32 v116, v116
	v_rcp_f32_e32 v117, v117
	v_add_f32_e32 v118, 1.0, v118
	v_add_f32_e32 v119, 1.0, v119
	v_pk_fma_f32 v[126:127], v[126:127], v[210:211], v[206:207]
	v_lshlrev_b32_e32 v206, 16, v209
	v_and_b32_e32 v207, 0xffff0000, v209
	v_lshlrev_b32_e32 v208, 16, v213
	v_and_b32_e32 v209, 0xffff0000, v213
	v_rcp_f32_e32 v118, v118
	v_rcp_f32_e32 v119, v119
	v_add_f32_e32 v112, 1.0, v112
	v_add_f32_e32 v113, 1.0, v113
	v_pk_fma_f32 v[120:121], v[232:233], v[230:231], v[228:229]
	v_pk_fma_f32 v[122:123], v[122:123], v[208:209], v[206:207]
	v_lshl_add_u64 v[206:207], v[222:223], 2, s[2:3]
	v_rcp_f32_e32 v112, v112
	v_rcp_f32_e32 v113, v113
	flat_store_dwordx4 v[206:207], v[120:123] offset:16
	flat_store_dwordx4 v[206:207], v[124:127]
; __device__ __forceinline__ float bflo(unsigned u) { return __uint_as_float(u << 16); }
; __device__ __forceinline__ float bfhi(unsigned u) { return __uint_as_float(u & 0xffff0000u); }
;     __device__ __forceinline__ void operator()(const Acc& acc, const Unit& u, int wr, int wc, int fr, int fq) const {
;     ...
;             for (int m = 0; m < 4; ++m) {
;                 const int row = u.pm * 256 + ai * 128 + wr * 64 + m * 16 + fr;
;                 const float rs = rsqrtf(rsv[m] * (1.0f / DM) + EPS) * -1.4426950408889634f;
; #pragma unroll
;                 for (int bj = 0; bj < 2; ++bj) {
;                     const size_t off = (size_t)row * DM + colbase + 32 * bj;
;                     f32x4 h0 = hv[m][bj][0], h1 = hv[m][bj][1];
;                     const u32x4 p4 = pw[m][bj];
;                     const f32x4 a0 = acc[ai][bj][m][0], a1 = acc[ai][bj][m][1];
;                     h0.x += bflo(p4.x) * __builtin_amdgcn_rcpf(1.0f + __builtin_amdgcn_exp2f(a0.x * rs));
;                     h0.y += bfhi(p4.x) * __builtin_amdgcn_rcpf(1.0f + __builtin_amdgcn_exp2f(a0.y * rs));
;                     h0.z += bflo(p4.y) * __builtin_amdgcn_rcpf(1.0f + __builtin_amdgcn_exp2f(a0.z * rs));
;                     h0.w += bfhi(p4.y) * __builtin_amdgcn_rcpf(1.0f + __builtin_amdgcn_exp2f(a0.w * rs));
;                     h1.x += bflo(p4.z) * __builtin_amdgcn_rcpf(1.0f + __builtin_amdgcn_exp2f(a1.x * rs));
;                     h1.y += bfhi(p4.z) * __builtin_amdgcn_rcpf(1.0f + __builtin_amdgcn_exp2f(a1.y * rs));
;                     h1.z += bflo(p4.w) * __builtin_amdgcn_rcpf(1.0f + __builtin_amdgcn_exp2f(a1.z * rs));
;                     h1.w += bfhi(p4.w) * __builtin_amdgcn_rcpf(1.0f + __builtin_amdgcn_exp2f(a1.w * rs));
;                     *(f32x4*)(out + off) = h0; *(f32x4*)(out + off + 4) = h1;
	v_mul_f32_e32 v114, v114, v212
	v_lshlrev_b32_e32 v120, 16, v214
	v_and_b32_e32 v121, 0xffff0000, v214
	v_lshlrev_b32_e32 v122, 16, v218
	v_and_b32_e32 v123, 0xffff0000, v218
	v_pk_fma_f32 v[116:117], v[116:117], v[122:123], v[120:121]
	v_lshlrev_b32_e32 v120, 16, v215
	v_and_b32_e32 v121, 0xffff0000, v215
	v_lshlrev_b32_e32 v122, 16, v219
	v_and_b32_e32 v123, 0xffff0000, v219
	v_pk_fma_f32 v[118:119], v[118:119], v[122:123], v[120:121]
	v_lshlrev_b32_e32 v120, 16, v216
	v_and_b32_e32 v121, 0xffff0000, v216
	v_lshlrev_b32_e32 v122, 16, v220
	v_and_b32_e32 v123, 0xffff0000, v220
	v_pk_fma_f32 v[112:113], v[112:113], v[122:123], v[120:121]
	v_fmamk_f32 v123, v234, 0x3a000000, v205
	v_mul_f32_e32 v124, 0x4b800000, v123
	v_cmp_gt_f32_e32 vcc, s40, v123
	flat_store_dwordx4 v[206:207], v[116:119] offset:128
	v_mul_f32_e32 v115, v115, v212
	v_cndmask_b32_e32 v123, v123, v124, vcc
	v_rsq_f32_e32 v124, v123
	v_exp_f32_e32 v114, v114
	v_exp_f32_e32 v115, v115
	v_lshlrev_b32_e32 v120, 16, v217
	v_mul_f32_e32 v116, 0x45800000, v124
	v_cndmask_b32_e32 v116, v124, v116, vcc
	v_mul_f32_e32 v116, 0xbfb8aa3b, v116
	v_mul_f32_e32 v108, v108, v116
	v_mul_f32_e32 v109, v109, v116
	v_exp_f32_e32 v108, v108
	v_exp_f32_e32 v109, v109
	v_mul_f32_e32 v110, v110, v116
	v_mul_f32_e32 v111, v111, v116
	v_exp_f32_e32 v110, v110
	v_exp_f32_e32 v111, v111
	v_mul_f32_e32 v104, v104, v116
	v_mul_f32_e32 v105, v105, v116
	v_add_f32_e32 v114, 1.0, v114
	v_add_f32_e32 v115, 1.0, v115
	v_exp_f32_e32 v104, v104
	v_exp_f32_e32 v105, v105
	v_mul_f32_e32 v106, v106, v116
	v_mul_f32_e32 v107, v107, v116
	v_rcp_f32_e32 v114, v114
	v_rcp_f32_e32 v115, v115
	v_exp_f32_e32 v106, v106
	v_exp_f32_e32 v107, v107
	v_add_f32_e32 v108, 1.0, v108
	v_add_f32_e32 v109, 1.0, v109
	v_mul_f32_e32 v100, v100, v116
	v_mul_f32_e32 v101, v101, v116
	v_rcp_f32_e32 v108, v108
	v_rcp_f32_e32 v109, v109
	v_add_f32_e32 v110, 1.0, v110
	v_add_f32_e32 v111, 1.0, v111
	v_exp_f32_e32 v100, v100
	v_exp_f32_e32 v101, v101
	v_mul_f32_e32 v102, v102, v116
	v_mul_f32_e32 v103, v103, v116
	v_and_b32_e32 v121, 0xffff0000, v217
	v_lshlrev_b32_e32 v122, 16, v221
	v_and_b32_e32 v123, 0xffff0000, v221
	v_rcp_f32_e32 v110, v110
	v_rcp_f32_e32 v111, v111
	v_add_f32_e32 v104, 1.0, v104
	v_add_f32_e32 v105, 1.0, v105
	v_exp_f32_e32 v102, v102
	v_exp_f32_e32 v103, v103
	v_mul_f32_e32 v96, v96, v116
	v_mul_f32_e32 v97, v97, v116
	v_pk_fma_f32 v[114:115], v[114:115], v[122:123], v[120:121]
	v_rcp_f32_e32 v104, v104
	v_rcp_f32_e32 v105, v105
	v_add_f32_e32 v106, 1.0, v106
	v_add_f32_e32 v107, 1.0, v107
	v_exp_f32_e32 v96, v96
	v_exp_f32_e32 v97, v97
	flat_store_dwordx4 v[206:207], v[112:115] offset:144
	v_rcp_f32_e32 v106, v106
	v_rcp_f32_e32 v107, v107
	v_lshlrev_b32_e32 v112, 16, v172
	v_and_b32_e32 v113, 0xffff0000, v172
	v_lshlrev_b32_e32 v114, 16, v168
	v_and_b32_e32 v115, 0xffff0000, v168
	v_pk_fma_f32 v[108:109], v[108:109], v[114:115], v[112:113]
	v_lshlrev_b32_e32 v112, 16, v173
	v_and_b32_e32 v113, 0xffff0000, v173
	v_lshlrev_b32_e32 v114, 16, v169
	v_and_b32_e32 v115, 0xffff0000, v169
	v_add_f32_e32 v100, 1.0, v100
	v_add_f32_e32 v101, 1.0, v101
	v_pk_fma_f32 v[110:111], v[110:111], v[114:115], v[112:113]
	v_lshlrev_b32_e32 v112, 16, v174
	v_and_b32_e32 v113, 0xffff0000, v174
	v_lshlrev_b32_e32 v114, 16, v170
	v_and_b32_e32 v115, 0xffff0000, v170
	v_rcp_f32_e32 v100, v100
	v_rcp_f32_e32 v101, v101
	v_add_f32_e32 v102, 1.0, v102
	v_add_f32_e32 v103, 1.0, v103
	v_pk_fma_f32 v[104:105], v[104:105], v[114:115], v[112:113]
	v_lshlrev_b32_e32 v112, 16, v175
	v_and_b32_e32 v113, 0xffff0000, v175
	v_lshlrev_b32_e32 v114, 16, v171
	v_and_b32_e32 v115, 0xffff0000, v171
	v_rcp_f32_e32 v102, v102
	v_rcp_f32_e32 v103, v103
	v_add_f32_e32 v96, 1.0, v96
	v_add_f32_e32 v97, 1.0, v97
	v_pk_fma_f32 v[106:107], v[106:107], v[114:115], v[112:113]
	v_lshl_add_u64 v[112:113], v[198:199], 2, s[2:3]
	v_rcp_f32_e32 v96, v96
	v_rcp_f32_e32 v97, v97
	flat_store_dwordx4 v[112:113], v[104:107] offset:16
	flat_store_dwordx4 v[112:113], v[108:111]
	v_mul_f32_e32 v98, v98, v116
	v_lshlrev_b32_e32 v104, 16, v164
	v_and_b32_e32 v105, 0xffff0000, v164
	v_lshlrev_b32_e32 v106, 16, v160
	v_and_b32_e32 v107, 0xffff0000, v160
	v_pk_fma_f32 v[100:101], v[100:101], v[106:107], v[104:105]
	v_lshlrev_b32_e32 v104, 16, v165
	v_and_b32_e32 v105, 0xffff0000, v165
	v_lshlrev_b32_e32 v106, 16, v161
	v_and_b32_e32 v107, 0xffff0000, v161
	v_pk_fma_f32 v[102:103], v[102:103], v[106:107], v[104:105]
	v_lshlrev_b32_e32 v104, 16, v166
	v_and_b32_e32 v105, 0xffff0000, v166
	v_lshlrev_b32_e32 v106, 16, v162
	v_and_b32_e32 v107, 0xffff0000, v162
	v_pk_fma_f32 v[96:97], v[96:97], v[106:107], v[104:105]
	v_fmamk_f32 v107, v235, 0x3a000000, v205
	v_mul_f32_e32 v108, 0x4b800000, v107
	v_cmp_gt_f32_e32 vcc, s40, v107
	flat_store_dwordx4 v[112:113], v[100:103] offset:128
	v_mul_f32_e32 v99, v99, v116
	v_cndmask_b32_e32 v107, v107, v108, vcc
	v_rsq_f32_e32 v108, v107
	v_exp_f32_e32 v98, v98
	v_exp_f32_e32 v99, v99
	v_lshlrev_b32_e32 v104, 16, v167
	v_mul_f32_e32 v100, 0x45800000, v108
	v_cndmask_b32_e32 v100, v108, v100, vcc
	v_mul_f32_e32 v100, 0xbfb8aa3b, v100
	v_mul_f32_e32 v92, v92, v100
	v_mul_f32_e32 v93, v93, v100
	v_exp_f32_e32 v92, v92
	v_exp_f32_e32 v93, v93
	v_mul_f32_e32 v94, v94, v100
	v_mul_f32_e32 v95, v95, v100
	v_exp_f32_e32 v94, v94
	v_exp_f32_e32 v95, v95
	v_mul_f32_e32 v88, v88, v100
	v_mul_f32_e32 v89, v89, v100
	v_add_f32_e32 v98, 1.0, v98
	v_add_f32_e32 v99, 1.0, v99
	v_exp_f32_e32 v88, v88
	v_exp_f32_e32 v89, v89
	v_mul_f32_e32 v90, v90, v100
	v_mul_f32_e32 v91, v91, v100
	v_rcp_f32_e32 v98, v98
	v_rcp_f32_e32 v99, v99
	v_exp_f32_e32 v90, v90
; __device__ __forceinline__ float bflo(unsigned u) { return __uint_as_float(u << 16); }
; __device__ __forceinline__ float bfhi(unsigned u) { return __uint_as_float(u & 0xffff0000u); }
;     __device__ __forceinline__ void operator()(const Acc& acc, const Unit& u, int wr, int wc, int fr, int fq) const {
;     ...
;             for (int m = 0; m < 4; ++m) {
;                 const int row = u.pm * 256 + ai * 128 + wr * 64 + m * 16 + fr;
;                 const float rs = rsqrtf(rsv[m] * (1.0f / DM) + EPS) * -1.4426950408889634f;
; #pragma unroll
;                 for (int bj = 0; bj < 2; ++bj) {
;                     const size_t off = (size_t)row * DM + colbase + 32 * bj;
;                     f32x4 h0 = hv[m][bj][0], h1 = hv[m][bj][1];
;                     const u32x4 p4 = pw[m][bj];
;                     const f32x4 a0 = acc[ai][bj][m][0], a1 = acc[ai][bj][m][1];
;                     h0.x += bflo(p4.x) * __builtin_amdgcn_rcpf(1.0f + __builtin_amdgcn_exp2f(a0.x * rs));
;                     h0.y += bfhi(p4.x) * __builtin_amdgcn_rcpf(1.0f + __builtin_amdgcn_exp2f(a0.y * rs));
;                     h0.z += bflo(p4.y) * __builtin_amdgcn_rcpf(1.0f + __builtin_amdgcn_exp2f(a0.z * rs));
;                     h0.w += bfhi(p4.y) * __builtin_amdgcn_rcpf(1.0f + __builtin_amdgcn_exp2f(a0.w * rs));
;                     h1.x += bflo(p4.z) * __builtin_amdgcn_rcpf(1.0f + __builtin_amdgcn_exp2f(a1.x * rs));
;                     h1.y += bfhi(p4.z) * __builtin_amdgcn_rcpf(1.0f + __builtin_amdgcn_exp2f(a1.y * rs));
;                     h1.z += bflo(p4.w) * __builtin_amdgcn_rcpf(1.0f + __builtin_amdgcn_exp2f(a1.z * rs));
;                     h1.w += bfhi(p4.w) * __builtin_amdgcn_rcpf(1.0f + __builtin_amdgcn_exp2f(a1.w * rs));
;                     *(f32x4*)(out + off) = h0; *(f32x4*)(out + off + 4) = h1;
	v_exp_f32_e32 v91, v91
	v_add_f32_e32 v92, 1.0, v92
	v_add_f32_e32 v93, 1.0, v93
	v_mul_f32_e32 v84, v84, v100
	v_mul_f32_e32 v85, v85, v100
	v_rcp_f32_e32 v92, v92
	v_rcp_f32_e32 v93, v93
	v_add_f32_e32 v94, 1.0, v94
	v_add_f32_e32 v95, 1.0, v95
	v_exp_f32_e32 v84, v84
	v_exp_f32_e32 v85, v85
	v_mul_f32_e32 v86, v86, v100
	v_mul_f32_e32 v87, v87, v100
	v_and_b32_e32 v105, 0xffff0000, v167
	v_lshlrev_b32_e32 v106, 16, v163
	v_and_b32_e32 v107, 0xffff0000, v163
	v_rcp_f32_e32 v94, v94
	v_rcp_f32_e32 v95, v95
	v_add_f32_e32 v88, 1.0, v88
	v_add_f32_e32 v89, 1.0, v89
	v_exp_f32_e32 v86, v86
	v_exp_f32_e32 v87, v87
	v_mul_f32_e32 v80, v80, v100
	v_mul_f32_e32 v81, v81, v100
	v_pk_fma_f32 v[98:99], v[98:99], v[106:107], v[104:105]
	v_rcp_f32_e32 v88, v88
	v_rcp_f32_e32 v89, v89
	v_add_f32_e32 v90, 1.0, v90
	v_add_f32_e32 v91, 1.0, v91
	v_exp_f32_e32 v80, v80
	v_exp_f32_e32 v81, v81
	flat_store_dwordx4 v[112:113], v[96:99] offset:144
	v_rcp_f32_e32 v90, v90
	v_rcp_f32_e32 v91, v91
	v_lshlrev_b32_e32 v96, 16, v156
	v_and_b32_e32 v97, 0xffff0000, v156
	v_lshlrev_b32_e32 v98, 16, v152
	v_and_b32_e32 v99, 0xffff0000, v152
	v_pk_fma_f32 v[92:93], v[92:93], v[98:99], v[96:97]
	v_lshlrev_b32_e32 v96, 16, v157
	v_and_b32_e32 v97, 0xffff0000, v157
	v_lshlrev_b32_e32 v98, 16, v153
	v_and_b32_e32 v99, 0xffff0000, v153
	v_add_f32_e32 v84, 1.0, v84
	v_add_f32_e32 v85, 1.0, v85
	v_pk_fma_f32 v[94:95], v[94:95], v[98:99], v[96:97]
	v_lshlrev_b32_e32 v96, 16, v158
	v_and_b32_e32 v97, 0xffff0000, v158
	v_lshlrev_b32_e32 v98, 16, v154
	v_and_b32_e32 v99, 0xffff0000, v154
	v_rcp_f32_e32 v84, v84
	v_rcp_f32_e32 v85, v85
	v_add_f32_e32 v86, 1.0, v86
	v_add_f32_e32 v87, 1.0, v87
	v_pk_fma_f32 v[88:89], v[88:89], v[98:99], v[96:97]
	v_lshlrev_b32_e32 v96, 16, v159
	v_and_b32_e32 v97, 0xffff0000, v159
	v_lshlrev_b32_e32 v98, 16, v155
	v_and_b32_e32 v99, 0xffff0000, v155
	v_rcp_f32_e32 v86, v86
	v_rcp_f32_e32 v87, v87
	v_add_f32_e32 v80, 1.0, v80
	v_add_f32_e32 v81, 1.0, v81
	v_pk_fma_f32 v[90:91], v[90:91], v[98:99], v[96:97]
	v_lshl_add_u64 v[96:97], v[196:197], 2, s[2:3]
	v_rcp_f32_e32 v80, v80
	v_rcp_f32_e32 v81, v81
	flat_store_dwordx4 v[96:97], v[88:91] offset:16
	flat_store_dwordx4 v[96:97], v[92:95]
	v_mul_f32_e32 v82, v82, v100
	v_lshlrev_b32_e32 v88, 16, v148
	v_and_b32_e32 v89, 0xffff0000, v148
	v_lshlrev_b32_e32 v90, 16, v144
	v_and_b32_e32 v91, 0xffff0000, v144
	v_pk_fma_f32 v[84:85], v[84:85], v[90:91], v[88:89]
	v_lshlrev_b32_e32 v88, 16, v149
	v_and_b32_e32 v89, 0xffff0000, v149
	v_lshlrev_b32_e32 v90, 16, v145
	v_and_b32_e32 v91, 0xffff0000, v145
	v_pk_fma_f32 v[86:87], v[86:87], v[90:91], v[88:89]
	v_lshlrev_b32_e32 v88, 16, v150
	v_and_b32_e32 v89, 0xffff0000, v150
	v_lshlrev_b32_e32 v90, 16, v146
	v_and_b32_e32 v91, 0xffff0000, v146
	v_pk_fma_f32 v[80:81], v[80:81], v[90:91], v[88:89]
	v_fmamk_f32 v91, v191, 0x3a000000, v205
	v_mul_f32_e32 v92, 0x4b800000, v91
	v_cmp_gt_f32_e32 vcc, s40, v91
	flat_store_dwordx4 v[96:97], v[84:87] offset:128
	v_mul_f32_e32 v83, v83, v100
	v_cndmask_b32_e32 v91, v91, v92, vcc
	v_rsq_f32_e32 v92, v91
	v_exp_f32_e32 v82, v82
	v_exp_f32_e32 v83, v83
	v_lshlrev_b32_e32 v88, 16, v151
	v_mul_f32_e32 v84, 0x45800000, v92
	v_cndmask_b32_e32 v84, v92, v84, vcc
	v_mul_f32_e32 v84, 0xbfb8aa3b, v84
	v_mul_f32_e32 v76, v76, v84
	v_mul_f32_e32 v77, v77, v84
	v_exp_f32_e32 v76, v76
	v_exp_f32_e32 v77, v77
	v_mul_f32_e32 v78, v78, v84
	v_mul_f32_e32 v79, v79, v84
	v_exp_f32_e32 v78, v78
	v_exp_f32_e32 v79, v79
	v_mul_f32_e32 v72, v72, v84
	v_mul_f32_e32 v73, v73, v84
	v_add_f32_e32 v82, 1.0, v82
	v_add_f32_e32 v83, 1.0, v83
	v_exp_f32_e32 v72, v72
	v_exp_f32_e32 v73, v73
	v_mul_f32_e32 v74, v74, v84
	v_mul_f32_e32 v75, v75, v84
	v_rcp_f32_e32 v82, v82
	v_rcp_f32_e32 v83, v83
	v_exp_f32_e32 v74, v74
	v_exp_f32_e32 v75, v75
	v_add_f32_e32 v76, 1.0, v76
	v_add_f32_e32 v77, 1.0, v77
	v_mul_f32_e32 v68, v68, v84
	v_mul_f32_e32 v69, v69, v84
	v_rcp_f32_e32 v76, v76
	v_rcp_f32_e32 v77, v77
	v_add_f32_e32 v78, 1.0, v78
	v_add_f32_e32 v79, 1.0, v79
	v_exp_f32_e32 v68, v68
	v_exp_f32_e32 v69, v69
	v_mul_f32_e32 v70, v70, v84
	v_mul_f32_e32 v71, v71, v84
	v_and_b32_e32 v89, 0xffff0000, v151
	v_lshlrev_b32_e32 v90, 16, v147
	v_and_b32_e32 v91, 0xffff0000, v147
	v_rcp_f32_e32 v78, v78
	v_rcp_f32_e32 v79, v79
	v_add_f32_e32 v72, 1.0, v72
	v_add_f32_e32 v73, 1.0, v73
	v_exp_f32_e32 v70, v70
	v_exp_f32_e32 v71, v71
	v_mul_f32_e32 v64, v64, v84
	v_mul_f32_e32 v65, v65, v84
	v_pk_fma_f32 v[82:83], v[82:83], v[90:91], v[88:89]
	v_rcp_f32_e32 v72, v72
	v_rcp_f32_e32 v73, v73
	v_add_f32_e32 v74, 1.0, v74
	v_add_f32_e32 v75, 1.0, v75
	v_exp_f32_e32 v64, v64
	v_exp_f32_e32 v65, v65
	v_mul_f32_e32 v66, v66, v84
	v_mul_f32_e32 v67, v67, v84
	flat_store_dwordx4 v[96:97], v[80:83] offset:144
	v_rcp_f32_e32 v74, v74
	v_rcp_f32_e32 v75, v75
	v_lshlrev_b32_e32 v80, 16, v140
	v_and_b32_e32 v81, 0xffff0000, v140
	v_lshlrev_b32_e32 v82, 16, v136
	v_and_b32_e32 v83, 0xffff0000, v136
	v_exp_f32_e32 v66, v66
	v_exp_f32_e32 v67, v67
	v_pk_fma_f32 v[76:77], v[76:77], v[82:83], v[80:81]
	v_lshlrev_b32_e32 v80, 16, v141
	v_and_b32_e32 v81, 0xffff0000, v141
	v_lshlrev_b32_e32 v82, 16, v137
	v_and_b32_e32 v83, 0xffff0000, v137
	v_add_f32_e32 v68, 1.0, v68
	v_add_f32_e32 v69, 1.0, v69
	v_pk_fma_f32 v[78:79], v[78:79], v[82:83], v[80:81]
	v_lshlrev_b32_e32 v80, 16, v142
	v_and_b32_e32 v81, 0xffff0000, v142
	v_lshlrev_b32_e32 v82, 16, v138
	v_and_b32_e32 v83, 0xffff0000, v138
	v_rcp_f32_e32 v68, v68
	v_rcp_f32_e32 v69, v69
	v_add_f32_e32 v70, 1.0, v70
	v_add_f32_e32 v71, 1.0, v71
	v_pk_fma_f32 v[72:73], v[72:73], v[82:83], v[80:81]
	v_lshlrev_b32_e32 v80, 16, v143
; __device__ __forceinline__ float bflo(unsigned u) { return __uint_as_float(u << 16); }
;     __device__ __forceinline__ void operator()(const Acc& acc, const Unit& u, int wr, int wc, int fr, int fq) const {
;     ...
;             for (int m = 0; m < 4; ++m) { const int row = u.pm * 256 + ai * 128 + wr * 64 + m * 16 + fr; const size_t off = (size_t)row * DM + colbase;
;                 rsv[m] = rowss[row];
; #pragma unroll
;                 for (int bj = 0; bj < 2; ++bj) { const u32x4 hw = __builtin_nontemporal_load((const u32x4*)(hin + off + 32 * bj));
;                     hv[m][bj][0] = (f32x4){bflo(hw.x), bfhi(hw.x), bflo(hw.y), bfhi(hw.y)}; hv[m][bj][1] = (f32x4){bflo(hw.z), bfhi(hw.z), bflo(hw.w), bfhi(hw.w)};
;                     pw[m][bj] = __builtin_nontemporal_load((const u32x4*)(PP + off + 32 * bj)); } }
; #pragma unroll
;             for (int m = 0; m < 4; ++m) {
;                 const int row = u.pm * 256 + ai * 128 + wr * 64 + m * 16 + fr;
;                 const float rs = rsqrtf(rsv[m] * (1.0f / DM) + EPS) * -1.4426950408889634f;
; #pragma unroll
;                 for (int bj = 0; bj < 2; ++bj) {
;                     const size_t off = (size_t)row * DM + colbase + 32 * bj;
;                     f32x4 h0 = hv[m][bj][0], h1 = hv[m][bj][1];
;                     const u32x4 p4 = pw[m][bj];
;                     const f32x4 a0 = acc[ai][bj][m][0], a1 = acc[ai][bj][m][1];
;                     h0.x += bflo(p4.x) * __builtin_amdgcn_rcpf(1.0f + __builtin_amdgcn_exp2f(a0.x * rs));
;                     h0.y += bfhi(p4.x) * __builtin_amdgcn_rcpf(1.0f + __builtin_amdgcn_exp2f(a0.y * rs));
;                     h0.z += bflo(p4.y) * __builtin_amdgcn_rcpf(1.0f + __builtin_amdgcn_exp2f(a0.z * rs));
;                     h0.w += bfhi(p4.y) * __builtin_amdgcn_rcpf(1.0f + __builtin_amdgcn_exp2f(a0.w * rs));
;                     h1.x += bflo(p4.z) * __builtin_amdgcn_rcpf(1.0f + __builtin_amdgcn_exp2f(a1.x * rs));
;                     h1.y += bfhi(p4.z) * __builtin_amdgcn_rcpf(1.0f + __builtin_amdgcn_exp2f(a1.y * rs));
;                     h1.z += bflo(p4.w) * __builtin_amdgcn_rcpf(1.0f + __builtin_amdgcn_exp2f(a1.z * rs));
;                     h1.w += bfhi(p4.w) * __builtin_amdgcn_rcpf(1.0f + __builtin_amdgcn_exp2f(a1.w * rs));
;                     *(f32x4*)(out + off) = h0; *(f32x4*)(out + off + 4) = h1;
	v_and_b32_e32 v81, 0xffff0000, v143
	v_lshlrev_b32_e32 v82, 16, v139
	v_and_b32_e32 v83, 0xffff0000, v139
	v_rcp_f32_e32 v70, v70
	v_rcp_f32_e32 v71, v71
	v_add_f32_e32 v64, 1.0, v64
	v_add_f32_e32 v65, 1.0, v65
	v_pk_fma_f32 v[74:75], v[74:75], v[82:83], v[80:81]
	v_lshl_add_u64 v[80:81], v[194:195], 2, s[2:3]
	v_rcp_f32_e32 v64, v64
	v_rcp_f32_e32 v65, v65
	v_add_f32_e32 v66, 1.0, v66
	v_add_f32_e32 v67, 1.0, v67
	flat_store_dwordx4 v[80:81], v[72:75] offset:16
	v_rcp_f32_e32 v66, v66
	v_rcp_f32_e32 v67, v67
	v_lshlrev_b32_e32 v72, 16, v132
	v_and_b32_e32 v73, 0xffff0000, v132
	v_lshlrev_b32_e32 v74, 16, v128
	v_and_b32_e32 v75, 0xffff0000, v128
	v_pk_fma_f32 v[68:69], v[68:69], v[74:75], v[72:73]
	v_lshlrev_b32_e32 v72, 16, v133
	v_and_b32_e32 v73, 0xffff0000, v133
	v_lshlrev_b32_e32 v74, 16, v129
	v_and_b32_e32 v75, 0xffff0000, v129
	v_pk_fma_f32 v[70:71], v[70:71], v[74:75], v[72:73]
	v_lshlrev_b32_e32 v72, 16, v134
	v_and_b32_e32 v73, 0xffff0000, v134
	v_lshlrev_b32_e32 v74, 16, v130
	v_and_b32_e32 v75, 0xffff0000, v130
	v_pk_fma_f32 v[64:65], v[64:65], v[74:75], v[72:73]
	v_lshlrev_b32_e32 v72, 16, v135
	v_and_b32_e32 v73, 0xffff0000, v135
	v_lshlrev_b32_e32 v74, 16, v131
	v_and_b32_e32 v75, 0xffff0000, v131
	flat_store_dwordx4 v[80:81], v[76:79]
	v_pk_fma_f32 v[66:67], v[66:67], v[74:75], v[72:73]
	flat_store_dwordx4 v[80:81], v[68:71] offset:128
	flat_store_dwordx4 v[80:81], v[64:67] offset:144
	flat_load_dword v68, v[192:193] offset:512
	s_nop 0
	v_add_u32_e32 v64, 0x80, v190
	v_ashrrev_i32_e32 v65, 31, v64
	v_lshlrev_b64 v[64:65], 11, v[64:65]
	v_lshl_add_u64 v[136:137], v[64:65], 0, v[188:189]
	v_lshlrev_b64 v[64:65], 1, v[136:137]
	v_lshl_add_u64 v[66:67], s[6:7], 0, v[64:65]
	v_lshl_add_u64 v[64:65], s[8:9], 0, v[64:65]
	v_mov_b64_e32 v[124:125], v[248:249]
	v_mov_b64_e32 v[126:127], v[252:253]
	flat_load_dwordx4 v[128:131], v[64:65] nt
	v_mov_b64_e32 v[132:133], v[236:237]
	v_mov_b64_e32 v[134:135], v[238:239]
	flat_load_dwordx4 v[112:115], v[64:65] offset:64 nt
	v_add_u32_e32 v64, 0x90, v190
	v_ashrrev_i32_e32 v65, 31, v64
	v_lshlrev_b64 v[64:65], 11, v[64:65]
	v_lshl_add_u64 v[120:121], v[64:65], 0, v[188:189]
	v_lshlrev_b64 v[64:65], 1, v[120:121]
	v_lshl_add_u64 v[66:67], s[6:7], 0, v[64:65]
	v_lshl_add_u64 v[64:65], s[8:9], 0, v[64:65]
	flat_load_dwordx4 v[108:111], v[66:67] nt
	flat_load_dwordx4 v[100:103], v[66:67] offset:64 nt
	flat_load_dwordx4 v[104:107], v[64:65] nt
	flat_load_dwordx4 v[96:99], v[64:65] offset:64 nt
	v_add_u32_e32 v64, 0xa0, v190
	v_ashrrev_i32_e32 v65, 31, v64
	v_lshlrev_b64 v[64:65], 11, v[64:65]
	v_lshl_add_u64 v[118:119], v[64:65], 0, v[188:189]
	v_lshlrev_b64 v[64:65], 1, v[118:119]
	v_lshl_add_u64 v[66:67], s[6:7], 0, v[64:65]
	v_lshl_add_u64 v[64:65], s[8:9], 0, v[64:65]
	flat_load_dwordx4 v[92:95], v[66:67] nt
	flat_load_dwordx4 v[84:87], v[66:67] offset:64 nt
	flat_load_dwordx4 v[88:91], v[64:65] nt
	flat_load_dwordx4 v[80:83], v[64:65] offset:64 nt
	flat_load_dword v123, v[192:193] offset:576
	flat_load_dword v142, v[192:193] offset:640
	flat_load_dword v122, v[192:193] offset:704
	v_add_u32_e32 v64, 0xb0, v190
	v_ashrrev_i32_e32 v65, 31, v64
	v_lshlrev_b64 v[64:65], 11, v[64:65]
	v_lshl_add_u64 v[116:117], v[64:65], 0, v[188:189]
	v_lshlrev_b64 v[64:65], 1, v[116:117]
	v_lshl_add_u64 v[66:67], s[6:7], 0, v[64:65]
	s_waitcnt vmcnt(0) lgkmcnt(0)
	v_fmamk_f32 v68, v68, 0x3a000000, v205
	v_mul_f32_e32 v69, 0x4b800000, v68
	v_cmp_gt_f32_e32 vcc, s40, v68
	v_lshlrev_b32_e32 v140, 16, v128
	s_nop 0
	v_cndmask_b32_e32 v68, v68, v69, vcc
	v_rsq_f32_e32 v70, v68
	v_lshl_add_u64 v[68:69], s[8:9], 0, v[64:65]
	v_lshlrev_b32_e32 v138, 16, v124
	v_and_b32_e32 v139, 0xffff0000, v124
	v_mul_f32_e32 v71, 0x45800000, v70
	v_cndmask_b32_e32 v70, v70, v71, vcc
	v_mul_f32_e32 v143, 0xbfb8aa3b, v70
	v_mul_f32_e32 v62, v62, v143
	v_mul_f32_e32 v63, v63, v143
	v_exp_f32_e32 v62, v62
	v_exp_f32_e32 v63, v63
	v_mul_f32_e32 v56, v56, v143
	v_mul_f32_e32 v57, v57, v143
	v_exp_f32_e32 v56, v56
	v_exp_f32_e32 v57, v57
	v_mul_f32_e32 v58, v58, v143
	v_mul_f32_e32 v59, v59, v143
	v_exp_f32_e32 v58, v58
	v_exp_f32_e32 v59, v59
	v_mul_f32_e32 v52, v52, v143
	v_mul_f32_e32 v53, v53, v143
	v_add_f32_e32 v62, 1.0, v62
	v_add_f32_e32 v63, 1.0, v63
	v_exp_f32_e32 v52, v52
	v_exp_f32_e32 v53, v53
	v_mul_f32_e32 v54, v54, v143
	v_mul_f32_e32 v55, v55, v143
	v_mul_f32_e32 v60, v60, v143
	v_mul_f32_e32 v61, v61, v143
	v_rcp_f32_e32 v62, v62
	v_rcp_f32_e32 v63, v63
	v_add_f32_e32 v56, 1.0, v56
	v_add_f32_e32 v57, 1.0, v57
	v_exp_f32_e32 v54, v54
	v_exp_f32_e32 v55, v55
	v_mul_f32_e32 v48, v48, v143
	v_mul_f32_e32 v49, v49, v143
	v_exp_f32_e32 v60, v60
	v_exp_f32_e32 v61, v61
	v_rcp_f32_e32 v56, v56
	v_rcp_f32_e32 v57, v57
	v_add_f32_e32 v58, 1.0, v58
	v_add_f32_e32 v59, 1.0, v59
	v_exp_f32_e32 v48, v48
	v_exp_f32_e32 v49, v49
	v_rcp_f32_e32 v58, v58
	v_rcp_f32_e32 v59, v59
	v_and_b32_e32 v141, 0xffff0000, v128
	v_lshlrev_b32_e32 v124, 16, v125
	v_and_b32_e32 v125, 0xffff0000, v125
	v_lshlrev_b32_e32 v128, 16, v129
	v_and_b32_e32 v129, 0xffff0000, v129
	v_add_f32_e32 v52, 1.0, v52
	v_add_f32_e32 v53, 1.0, v53
	flat_load_dwordx4 v[72:75], v[66:67] nt
	s_nop 0
	flat_load_dwordx4 v[64:67], v[66:67] offset:64 nt
	s_nop 0
	flat_load_dwordx4 v[76:79], v[68:69] nt
	s_nop 0
	flat_load_dwordx4 v[68:71], v[68:69] offset:64 nt
	v_pk_fma_f32 v[62:63], v[62:63], v[128:129], v[124:125]
	v_lshlrev_b32_e32 v124, 16, v126
	v_and_b32_e32 v125, 0xffff0000, v126
	v_lshlrev_b32_e32 v128, 16, v130
	v_and_b32_e32 v129, 0xffff0000, v130
	v_rcp_f32_e32 v52, v52
	v_rcp_f32_e32 v53, v53
	v_add_f32_e32 v54, 1.0, v54
	v_add_f32_e32 v55, 1.0, v55
; __device__ __forceinline__ float bflo(unsigned u) { return __uint_as_float(u << 16); }
; __device__ __forceinline__ float bfhi(unsigned u) { return __uint_as_float(u & 0xffff0000u); }
;     __device__ __forceinline__ void operator()(const Acc& acc, const Unit& u, int wr, int wc, int fr, int fq) const {
;     ...
;             for (int m = 0; m < 4; ++m) {
;                 const int row = u.pm * 256 + ai * 128 + wr * 64 + m * 16 + fr;
;                 const float rs = rsqrtf(rsv[m] * (1.0f / DM) + EPS) * -1.4426950408889634f;
; #pragma unroll
;                 for (int bj = 0; bj < 2; ++bj) {
;                     const size_t off = (size_t)row * DM + colbase + 32 * bj;
;                     f32x4 h0 = hv[m][bj][0], h1 = hv[m][bj][1];
;                     const u32x4 p4 = pw[m][bj];
;                     const f32x4 a0 = acc[ai][bj][m][0], a1 = acc[ai][bj][m][1];
;                     h0.x += bflo(p4.x) * __builtin_amdgcn_rcpf(1.0f + __builtin_amdgcn_exp2f(a0.x * rs));
;                     h0.y += bfhi(p4.x) * __builtin_amdgcn_rcpf(1.0f + __builtin_amdgcn_exp2f(a0.y * rs));
;                     h0.z += bflo(p4.y) * __builtin_amdgcn_rcpf(1.0f + __builtin_amdgcn_exp2f(a0.z * rs));
;                     h0.w += bfhi(p4.y) * __builtin_amdgcn_rcpf(1.0f + __builtin_amdgcn_exp2f(a0.w * rs));
;                     h1.x += bflo(p4.z) * __builtin_amdgcn_rcpf(1.0f + __builtin_amdgcn_exp2f(a1.x * rs));
;                     h1.y += bfhi(p4.z) * __builtin_amdgcn_rcpf(1.0f + __builtin_amdgcn_exp2f(a1.y * rs));
;                     h1.z += bflo(p4.w) * __builtin_amdgcn_rcpf(1.0f + __builtin_amdgcn_exp2f(a1.z * rs));
;                     h1.w += bfhi(p4.w) * __builtin_amdgcn_rcpf(1.0f + __builtin_amdgcn_exp2f(a1.w * rs));
;                     *(f32x4*)(out + off) = h0; *(f32x4*)(out + off + 4) = h1;
	v_add_f32_e32 v60, 1.0, v60
	v_add_f32_e32 v61, 1.0, v61
	v_pk_fma_f32 v[56:57], v[56:57], v[128:129], v[124:125]
	v_lshlrev_b32_e32 v124, 16, v127
	v_and_b32_e32 v125, 0xffff0000, v127
	v_lshlrev_b32_e32 v126, 16, v131
	v_and_b32_e32 v127, 0xffff0000, v131
	v_rcp_f32_e32 v54, v54
	v_rcp_f32_e32 v55, v55
	v_add_f32_e32 v48, 1.0, v48
	v_add_f32_e32 v49, 1.0, v49
	v_rcp_f32_e32 v60, v60
	v_rcp_f32_e32 v61, v61
	v_pk_fma_f32 v[58:59], v[58:59], v[126:127], v[124:125]
	v_lshl_add_u64 v[124:125], v[136:137], 2, s[2:3]
	v_rcp_f32_e32 v48, v48
	v_rcp_f32_e32 v49, v49
	flat_store_dwordx4 v[124:125], v[56:59] offset:16
	v_pk_fma_f32 v[60:61], v[60:61], v[140:141], v[138:139]
	flat_store_dwordx4 v[124:125], v[60:63]
	v_lshlrev_b32_e32 v56, 16, v132
	v_and_b32_e32 v57, 0xffff0000, v132
	v_lshlrev_b32_e32 v58, 16, v112
	v_and_b32_e32 v59, 0xffff0000, v112
	v_pk_fma_f32 v[52:53], v[52:53], v[58:59], v[56:57]
	v_lshlrev_b32_e32 v56, 16, v133
	v_and_b32_e32 v57, 0xffff0000, v133
	v_lshlrev_b32_e32 v58, 16, v113
	v_and_b32_e32 v59, 0xffff0000, v113
	v_pk_fma_f32 v[54:55], v[54:55], v[58:59], v[56:57]
	v_lshlrev_b32_e32 v56, 16, v134
	v_and_b32_e32 v57, 0xffff0000, v134
	v_lshlrev_b32_e32 v58, 16, v114
	v_and_b32_e32 v59, 0xffff0000, v114
	v_pk_fma_f32 v[48:49], v[48:49], v[58:59], v[56:57]
	v_fmamk_f32 v59, v123, 0x3a000000, v205
	v_mul_f32_e32 v60, 0x4b800000, v59
	v_cmp_gt_f32_e32 vcc, s40, v59
	flat_store_dwordx4 v[124:125], v[52:55] offset:128
	v_mul_f32_e32 v50, v50, v143
	v_cndmask_b32_e32 v59, v59, v60, vcc
	v_rsq_f32_e32 v60, v59
	v_mul_f32_e32 v51, v51, v143
	v_exp_f32_e32 v50, v50
	v_exp_f32_e32 v51, v51
	v_mul_f32_e32 v52, 0x45800000, v60
	v_cndmask_b32_e32 v52, v60, v52, vcc
	v_mul_f32_e32 v52, 0xbfb8aa3b, v52
	v_mul_f32_e32 v44, v44, v52
	v_mul_f32_e32 v45, v45, v52
	v_exp_f32_e32 v44, v44
	v_exp_f32_e32 v45, v45
	v_mul_f32_e32 v46, v46, v52
	v_mul_f32_e32 v47, v47, v52
	v_exp_f32_e32 v46, v46
	v_exp_f32_e32 v47, v47
	v_mul_f32_e32 v40, v40, v52
	v_mul_f32_e32 v41, v41, v52
	v_add_f32_e32 v50, 1.0, v50
	v_add_f32_e32 v51, 1.0, v51
	v_exp_f32_e32 v40, v40
	v_exp_f32_e32 v41, v41
	v_mul_f32_e32 v42, v42, v52
	v_mul_f32_e32 v43, v43, v52
	v_rcp_f32_e32 v50, v50
	v_rcp_f32_e32 v51, v51
	v_exp_f32_e32 v42, v42
	v_exp_f32_e32 v43, v43
	v_add_f32_e32 v44, 1.0, v44
	v_add_f32_e32 v45, 1.0, v45
	v_mul_f32_e32 v36, v36, v52
	v_mul_f32_e32 v37, v37, v52
	v_rcp_f32_e32 v44, v44
	v_rcp_f32_e32 v45, v45
	v_add_f32_e32 v46, 1.0, v46
	v_add_f32_e32 v47, 1.0, v47
	v_exp_f32_e32 v36, v36
	v_exp_f32_e32 v37, v37
	v_mul_f32_e32 v38, v38, v52
	v_mul_f32_e32 v39, v39, v52
	v_lshlrev_b32_e32 v56, 16, v135
	v_and_b32_e32 v57, 0xffff0000, v135
	v_lshlrev_b32_e32 v58, 16, v115
	v_and_b32_e32 v59, 0xffff0000, v115
	v_rcp_f32_e32 v46, v46
	v_rcp_f32_e32 v47, v47
	v_add_f32_e32 v40, 1.0, v40
	v_add_f32_e32 v41, 1.0, v41
	v_exp_f32_e32 v38, v38
	v_exp_f32_e32 v39, v39
	v_mul_f32_e32 v32, v32, v52
	v_mul_f32_e32 v33, v33, v52
	v_pk_fma_f32 v[50:51], v[50:51], v[58:59], v[56:57]
	v_rcp_f32_e32 v40, v40
	v_rcp_f32_e32 v41, v41
	v_add_f32_e32 v42, 1.0, v42
	v_add_f32_e32 v43, 1.0, v43
	v_exp_f32_e32 v32, v32
	v_exp_f32_e32 v33, v33
	flat_store_dwordx4 v[124:125], v[48:51] offset:144
	v_rcp_f32_e32 v42, v42
	v_rcp_f32_e32 v43, v43
	v_lshlrev_b32_e32 v48, 16, v108
	v_and_b32_e32 v49, 0xffff0000, v108
	v_lshlrev_b32_e32 v50, 16, v104
	v_and_b32_e32 v51, 0xffff0000, v104
	v_pk_fma_f32 v[44:45], v[44:45], v[50:51], v[48:49]
	v_lshlrev_b32_e32 v48, 16, v109
	v_and_b32_e32 v49, 0xffff0000, v109
	v_lshlrev_b32_e32 v50, 16, v105
	v_and_b32_e32 v51, 0xffff0000, v105
	v_add_f32_e32 v36, 1.0, v36
	v_add_f32_e32 v37, 1.0, v37
	v_pk_fma_f32 v[46:47], v[46:47], v[50:51], v[48:49]
	v_lshlrev_b32_e32 v48, 16, v110
	v_and_b32_e32 v49, 0xffff0000, v110
	v_lshlrev_b32_e32 v50, 16, v106
	v_and_b32_e32 v51, 0xffff0000, v106
	v_rcp_f32_e32 v36, v36
	v_rcp_f32_e32 v37, v37
	v_add_f32_e32 v38, 1.0, v38
	v_add_f32_e32 v39, 1.0, v39
	v_pk_fma_f32 v[40:41], v[40:41], v[50:51], v[48:49]
	v_lshlrev_b32_e32 v48, 16, v111
	v_and_b32_e32 v49, 0xffff0000, v111
	v_lshlrev_b32_e32 v50, 16, v107
	v_and_b32_e32 v51, 0xffff0000, v107
	v_rcp_f32_e32 v38, v38
	v_rcp_f32_e32 v39, v39
	v_add_f32_e32 v32, 1.0, v32
	v_add_f32_e32 v33, 1.0, v33
	v_pk_fma_f32 v[42:43], v[42:43], v[50:51], v[48:49]
	v_lshl_add_u64 v[48:49], v[120:121], 2, s[2:3]
	v_rcp_f32_e32 v32, v32
	v_rcp_f32_e32 v33, v33
	flat_store_dwordx4 v[48:49], v[40:43] offset:16
	flat_store_dwordx4 v[48:49], v[44:47]
	v_mul_f32_e32 v34, v34, v52
	v_lshlrev_b32_e32 v40, 16, v100
	v_and_b32_e32 v41, 0xffff0000, v100
	v_lshlrev_b32_e32 v42, 16, v96
	v_and_b32_e32 v43, 0xffff0000, v96
	v_pk_fma_f32 v[36:37], v[36:37], v[42:43], v[40:41]
	v_lshlrev_b32_e32 v40, 16, v101
	v_and_b32_e32 v41, 0xffff0000, v101
	v_lshlrev_b32_e32 v42, 16, v97
	v_and_b32_e32 v43, 0xffff0000, v97
	v_pk_fma_f32 v[38:39], v[38:39], v[42:43], v[40:41]
	v_lshlrev_b32_e32 v40, 16, v102
	v_and_b32_e32 v41, 0xffff0000, v102
	v_lshlrev_b32_e32 v42, 16, v98
	v_and_b32_e32 v43, 0xffff0000, v98
	v_pk_fma_f32 v[32:33], v[32:33], v[42:43], v[40:41]
	v_fmamk_f32 v43, v142, 0x3a000000, v205
	v_mul_f32_e32 v44, 0x4b800000, v43
	v_cmp_gt_f32_e32 vcc, s40, v43
	flat_store_dwordx4 v[48:49], v[36:39] offset:128
	v_mul_f32_e32 v35, v35, v52
	v_cndmask_b32_e32 v43, v43, v44, vcc
	v_rsq_f32_e32 v44, v43
	v_exp_f32_e32 v34, v34
	v_exp_f32_e32 v35, v35
	v_lshlrev_b32_e32 v40, 16, v103
	v_mul_f32_e32 v36, 0x45800000, v44
	v_cndmask_b32_e32 v36, v44, v36, vcc
	v_mul_f32_e32 v36, 0xbfb8aa3b, v36
	v_mul_f32_e32 v28, v28, v36
	v_mul_f32_e32 v29, v29, v36
	v_exp_f32_e32 v28, v28
	v_exp_f32_e32 v29, v29
; __device__ __forceinline__ float bflo(unsigned u) { return __uint_as_float(u << 16); }
; __device__ __forceinline__ float bfhi(unsigned u) { return __uint_as_float(u & 0xffff0000u); }
;     __device__ __forceinline__ void operator()(const Acc& acc, const Unit& u, int wr, int wc, int fr, int fq) const {
;     ...
;             for (int m = 0; m < 4; ++m) {
;                 const int row = u.pm * 256 + ai * 128 + wr * 64 + m * 16 + fr;
;                 const float rs = rsqrtf(rsv[m] * (1.0f / DM) + EPS) * -1.4426950408889634f;
; #pragma unroll
;                 for (int bj = 0; bj < 2; ++bj) {
;                     const size_t off = (size_t)row * DM + colbase + 32 * bj;
;                     f32x4 h0 = hv[m][bj][0], h1 = hv[m][bj][1];
;                     const u32x4 p4 = pw[m][bj];
;                     const f32x4 a0 = acc[ai][bj][m][0], a1 = acc[ai][bj][m][1];
;                     h0.x += bflo(p4.x) * __builtin_amdgcn_rcpf(1.0f + __builtin_amdgcn_exp2f(a0.x * rs));
;                     h0.y += bfhi(p4.x) * __builtin_amdgcn_rcpf(1.0f + __builtin_amdgcn_exp2f(a0.y * rs));
;                     h0.z += bflo(p4.y) * __builtin_amdgcn_rcpf(1.0f + __builtin_amdgcn_exp2f(a0.z * rs));
;                     h0.w += bfhi(p4.y) * __builtin_amdgcn_rcpf(1.0f + __builtin_amdgcn_exp2f(a0.w * rs));
;                     h1.x += bflo(p4.z) * __builtin_amdgcn_rcpf(1.0f + __builtin_amdgcn_exp2f(a1.x * rs));
;                     h1.y += bfhi(p4.z) * __builtin_amdgcn_rcpf(1.0f + __builtin_amdgcn_exp2f(a1.y * rs));
;                     h1.z += bflo(p4.w) * __builtin_amdgcn_rcpf(1.0f + __builtin_amdgcn_exp2f(a1.z * rs));
;                     h1.w += bfhi(p4.w) * __builtin_amdgcn_rcpf(1.0f + __builtin_amdgcn_exp2f(a1.w * rs));
;                     *(f32x4*)(out + off) = h0; *(f32x4*)(out + off + 4) = h1;
	v_mul_f32_e32 v30, v30, v36
	v_mul_f32_e32 v31, v31, v36
	v_exp_f32_e32 v30, v30
	v_exp_f32_e32 v31, v31
	v_mul_f32_e32 v24, v24, v36
	v_mul_f32_e32 v25, v25, v36
	v_add_f32_e32 v34, 1.0, v34
	v_add_f32_e32 v35, 1.0, v35
	v_exp_f32_e32 v24, v24
	v_exp_f32_e32 v25, v25
	v_mul_f32_e32 v26, v26, v36
	v_mul_f32_e32 v27, v27, v36
	v_rcp_f32_e32 v34, v34
	v_rcp_f32_e32 v35, v35
	v_exp_f32_e32 v26, v26
	v_exp_f32_e32 v27, v27
	v_add_f32_e32 v28, 1.0, v28
	v_add_f32_e32 v29, 1.0, v29
	v_mul_f32_e32 v20, v20, v36
	v_mul_f32_e32 v21, v21, v36
	v_rcp_f32_e32 v28, v28
	v_rcp_f32_e32 v29, v29
	v_add_f32_e32 v30, 1.0, v30
	v_add_f32_e32 v31, 1.0, v31
	v_exp_f32_e32 v20, v20
	v_exp_f32_e32 v21, v21
	v_mul_f32_e32 v22, v22, v36
	v_mul_f32_e32 v23, v23, v36
	v_and_b32_e32 v41, 0xffff0000, v103
	v_lshlrev_b32_e32 v42, 16, v99
	v_and_b32_e32 v43, 0xffff0000, v99
	v_rcp_f32_e32 v30, v30
	v_rcp_f32_e32 v31, v31
	v_add_f32_e32 v24, 1.0, v24
	v_add_f32_e32 v25, 1.0, v25
	v_exp_f32_e32 v22, v22
	v_exp_f32_e32 v23, v23
	v_mul_f32_e32 v16, v16, v36
	v_mul_f32_e32 v17, v17, v36
	v_pk_fma_f32 v[34:35], v[34:35], v[42:43], v[40:41]
	v_rcp_f32_e32 v24, v24
	v_rcp_f32_e32 v25, v25
	v_add_f32_e32 v26, 1.0, v26
	v_add_f32_e32 v27, 1.0, v27
	v_exp_f32_e32 v16, v16
	v_exp_f32_e32 v17, v17
	flat_store_dwordx4 v[48:49], v[32:35] offset:144
	v_rcp_f32_e32 v26, v26
	v_rcp_f32_e32 v27, v27
	v_lshlrev_b32_e32 v32, 16, v92
	v_and_b32_e32 v33, 0xffff0000, v92
	v_lshlrev_b32_e32 v34, 16, v88
	v_and_b32_e32 v35, 0xffff0000, v88
	v_pk_fma_f32 v[28:29], v[28:29], v[34:35], v[32:33]
	v_lshlrev_b32_e32 v32, 16, v93
	v_and_b32_e32 v33, 0xffff0000, v93
	v_lshlrev_b32_e32 v34, 16, v89
	v_and_b32_e32 v35, 0xffff0000, v89
	v_add_f32_e32 v20, 1.0, v20
	v_add_f32_e32 v21, 1.0, v21
	v_pk_fma_f32 v[30:31], v[30:31], v[34:35], v[32:33]
	v_lshlrev_b32_e32 v32, 16, v94
	v_and_b32_e32 v33, 0xffff0000, v94
	v_lshlrev_b32_e32 v34, 16, v90
	v_and_b32_e32 v35, 0xffff0000, v90
	v_rcp_f32_e32 v20, v20
	v_rcp_f32_e32 v21, v21
	v_add_f32_e32 v22, 1.0, v22
	v_add_f32_e32 v23, 1.0, v23
	v_pk_fma_f32 v[24:25], v[24:25], v[34:35], v[32:33]
	v_lshlrev_b32_e32 v32, 16, v95
	v_and_b32_e32 v33, 0xffff0000, v95
	v_lshlrev_b32_e32 v34, 16, v91
	v_and_b32_e32 v35, 0xffff0000, v91
	v_rcp_f32_e32 v22, v22
	v_rcp_f32_e32 v23, v23
	v_add_f32_e32 v16, 1.0, v16
	v_add_f32_e32 v17, 1.0, v17
	v_pk_fma_f32 v[26:27], v[26:27], v[34:35], v[32:33]
	v_lshl_add_u64 v[32:33], v[118:119], 2, s[2:3]
	v_rcp_f32_e32 v16, v16
	v_rcp_f32_e32 v17, v17
	flat_store_dwordx4 v[32:33], v[24:27] offset:16
	flat_store_dwordx4 v[32:33], v[28:31]
	v_mul_f32_e32 v18, v18, v36
	v_lshlrev_b32_e32 v24, 16, v84
	v_and_b32_e32 v25, 0xffff0000, v84
	v_lshlrev_b32_e32 v26, 16, v80
	v_and_b32_e32 v27, 0xffff0000, v80
	v_pk_fma_f32 v[20:21], v[20:21], v[26:27], v[24:25]
	v_lshlrev_b32_e32 v24, 16, v85
	v_and_b32_e32 v25, 0xffff0000, v85
	v_lshlrev_b32_e32 v26, 16, v81
	v_and_b32_e32 v27, 0xffff0000, v81
	v_pk_fma_f32 v[22:23], v[22:23], v[26:27], v[24:25]
	v_lshlrev_b32_e32 v24, 16, v86
	v_and_b32_e32 v25, 0xffff0000, v86
	v_lshlrev_b32_e32 v26, 16, v82
	v_and_b32_e32 v27, 0xffff0000, v82
	v_pk_fma_f32 v[16:17], v[16:17], v[26:27], v[24:25]
	v_fmamk_f32 v27, v122, 0x3a000000, v205
	v_mul_f32_e32 v28, 0x4b800000, v27
	v_cmp_gt_f32_e32 vcc, s40, v27
	flat_store_dwordx4 v[32:33], v[20:23] offset:128
	v_mul_f32_e32 v19, v19, v36
	v_cndmask_b32_e32 v27, v27, v28, vcc
	v_rsq_f32_e32 v28, v27
	v_exp_f32_e32 v18, v18
	v_exp_f32_e32 v19, v19
	v_lshlrev_b32_e32 v24, 16, v87
	v_mul_f32_e32 v20, 0x45800000, v28
	v_cndmask_b32_e32 v20, v28, v20, vcc
	v_mul_f32_e32 v20, 0xbfb8aa3b, v20
	v_mul_f32_e32 v12, v12, v20
	v_mul_f32_e32 v13, v13, v20
	v_exp_f32_e32 v12, v12
	v_exp_f32_e32 v13, v13
	v_mul_f32_e32 v14, v14, v20
	v_mul_f32_e32 v15, v15, v20
	v_exp_f32_e32 v14, v14
	v_exp_f32_e32 v15, v15
	v_mul_f32_e32 v8, v8, v20
	v_mul_f32_e32 v9, v9, v20
	v_add_f32_e32 v18, 1.0, v18
	v_add_f32_e32 v19, 1.0, v19
	v_exp_f32_e32 v8, v8
	v_exp_f32_e32 v9, v9
	v_mul_f32_e32 v10, v10, v20
	v_mul_f32_e32 v11, v11, v20
	v_rcp_f32_e32 v18, v18
	v_rcp_f32_e32 v19, v19
	v_exp_f32_e32 v10, v10
	v_exp_f32_e32 v11, v11
	v_add_f32_e32 v12, 1.0, v12
	v_add_f32_e32 v13, 1.0, v13
	v_mul_f32_e32 v4, v4, v20
	v_mul_f32_e32 v5, v5, v20
	v_rcp_f32_e32 v12, v12
	v_rcp_f32_e32 v13, v13
	v_add_f32_e32 v14, 1.0, v14
	v_add_f32_e32 v15, 1.0, v15
	v_exp_f32_e32 v4, v4
	v_exp_f32_e32 v5, v5
	v_mul_f32_e32 v6, v6, v20
	v_mul_f32_e32 v7, v7, v20
	v_and_b32_e32 v25, 0xffff0000, v87
	v_lshlrev_b32_e32 v26, 16, v83
	v_and_b32_e32 v27, 0xffff0000, v83
	v_rcp_f32_e32 v14, v14
	v_rcp_f32_e32 v15, v15
	v_add_f32_e32 v8, 1.0, v8
	v_add_f32_e32 v9, 1.0, v9
	v_exp_f32_e32 v6, v6
	v_exp_f32_e32 v7, v7
	v_mul_f32_e32 v0, v0, v20
	v_mul_f32_e32 v1, v1, v20
	v_pk_fma_f32 v[18:19], v[18:19], v[26:27], v[24:25]
	v_rcp_f32_e32 v8, v8
	v_rcp_f32_e32 v9, v9
	v_add_f32_e32 v10, 1.0, v10
	v_add_f32_e32 v11, 1.0, v11
	v_exp_f32_e32 v0, v0
	v_exp_f32_e32 v1, v1
	v_mul_f32_e32 v2, v2, v20
	v_mul_f32_e32 v3, v3, v20
	flat_store_dwordx4 v[32:33], v[16:19] offset:144
	v_rcp_f32_e32 v10, v10
	v_rcp_f32_e32 v11, v11
	s_waitcnt vmcnt(0) lgkmcnt(0)
; __device__ __forceinline__ float bflo(unsigned u) { return __uint_as_float(u << 16); }
; __device__ __forceinline__ float bfhi(unsigned u) { return __uint_as_float(u & 0xffff0000u); }
; #define PG8_BAR __builtin_amdgcn_s_barrier()
; template <class Epi, bool ALIGN_EPI>
; __device__ __forceinline__ void gemm_phase(LAS unsigned char* lds, const Gemm g, const StaticOrder& S, const Epi& E, const int wid) {
;     ...
;         if (!has_next) break;
; #pragma unroll
;         for (int a = 0; a < 2; ++a)
; #pragma unroll
;             for (int b = 0; b < 2; ++b)
; #pragma unroll
;                 for (int m = 0; m < 4; ++m)
; #pragma unroll
;                     for (int n = 0; n < 2; ++n) acc[a][b][m][n] = (f32x4){0.f, 0.f, 0.f, 0.f};
;         cur = nxt; cA = nA; cB = nB; ++ui;
;         if constexpr (ALIGN_EPI) { if (wr == 1) PG8_BAR; }
;     __device__ __forceinline__ void operator()(const Acc& acc, const Unit& u, int wr, int wc, int fr, int fq) const {
;     ...
;                     h0.x += bflo(p4.x) * __builtin_amdgcn_rcpf(1.0f + __builtin_amdgcn_exp2f(a0.x * rs));
;                     h0.y += bfhi(p4.x) * __builtin_amdgcn_rcpf(1.0f + __builtin_amdgcn_exp2f(a0.y * rs));
;                     h0.z += bflo(p4.y) * __builtin_amdgcn_rcpf(1.0f + __builtin_amdgcn_exp2f(a0.z * rs));
;                     h0.w += bfhi(p4.y) * __builtin_amdgcn_rcpf(1.0f + __builtin_amdgcn_exp2f(a0.w * rs));
;                     h1.x += bflo(p4.z) * __builtin_amdgcn_rcpf(1.0f + __builtin_amdgcn_exp2f(a1.x * rs));
;                     h1.y += bfhi(p4.z) * __builtin_amdgcn_rcpf(1.0f + __builtin_amdgcn_exp2f(a1.y * rs));
;                     h1.z += bflo(p4.w) * __builtin_amdgcn_rcpf(1.0f + __builtin_amdgcn_exp2f(a1.z * rs));
;                     h1.w += bfhi(p4.w) * __builtin_amdgcn_rcpf(1.0f + __builtin_amdgcn_exp2f(a1.w * rs));
;                     *(f32x4*)(out + off) = h0; *(f32x4*)(out + off + 4) = h1;
	v_lshlrev_b32_e32 v16, 16, v72
	v_and_b32_e32 v17, 0xffff0000, v72
	v_lshlrev_b32_e32 v18, 16, v76
	v_and_b32_e32 v19, 0xffff0000, v76
	v_exp_f32_e32 v2, v2
	v_exp_f32_e32 v3, v3
	v_pk_fma_f32 v[12:13], v[12:13], v[18:19], v[16:17]
	v_lshlrev_b32_e32 v16, 16, v73
	v_and_b32_e32 v17, 0xffff0000, v73
	v_lshlrev_b32_e32 v18, 16, v77
	v_and_b32_e32 v19, 0xffff0000, v77
	v_add_f32_e32 v4, 1.0, v4
	v_add_f32_e32 v5, 1.0, v5
	v_pk_fma_f32 v[14:15], v[14:15], v[18:19], v[16:17]
	v_lshlrev_b32_e32 v16, 16, v74
	v_and_b32_e32 v17, 0xffff0000, v74
	v_lshlrev_b32_e32 v18, 16, v78
	v_and_b32_e32 v19, 0xffff0000, v78
	v_rcp_f32_e32 v4, v4
	v_rcp_f32_e32 v5, v5
	v_add_f32_e32 v6, 1.0, v6
	v_add_f32_e32 v7, 1.0, v7
	v_pk_fma_f32 v[8:9], v[8:9], v[18:19], v[16:17]
	v_lshlrev_b32_e32 v16, 16, v75
	v_and_b32_e32 v17, 0xffff0000, v75
	v_lshlrev_b32_e32 v18, 16, v79
	v_and_b32_e32 v19, 0xffff0000, v79
	v_rcp_f32_e32 v6, v6
	v_rcp_f32_e32 v7, v7
	v_add_f32_e32 v0, 1.0, v0
	v_add_f32_e32 v1, 1.0, v1
	v_pk_fma_f32 v[10:11], v[10:11], v[18:19], v[16:17]
	v_lshl_add_u64 v[16:17], v[116:117], 2, s[2:3]
	v_rcp_f32_e32 v0, v0
	v_rcp_f32_e32 v1, v1
	v_add_f32_e32 v2, 1.0, v2
	v_add_f32_e32 v3, 1.0, v3
	flat_store_dwordx4 v[16:17], v[8:11] offset:16
	v_rcp_f32_e32 v2, v2
	v_rcp_f32_e32 v3, v3
	v_lshlrev_b32_e32 v8, 16, v64
	v_and_b32_e32 v9, 0xffff0000, v64
	v_lshlrev_b32_e32 v10, 16, v68
	v_and_b32_e32 v11, 0xffff0000, v68
	v_pk_fma_f32 v[4:5], v[4:5], v[10:11], v[8:9]
	v_lshlrev_b32_e32 v8, 16, v65
	v_and_b32_e32 v9, 0xffff0000, v65
	v_lshlrev_b32_e32 v10, 16, v69
	v_and_b32_e32 v11, 0xffff0000, v69
	v_pk_fma_f32 v[6:7], v[6:7], v[10:11], v[8:9]
	v_lshlrev_b32_e32 v8, 16, v66
	v_and_b32_e32 v9, 0xffff0000, v66
	v_lshlrev_b32_e32 v10, 16, v70
	v_and_b32_e32 v11, 0xffff0000, v70
	v_pk_fma_f32 v[0:1], v[0:1], v[10:11], v[8:9]
	v_lshlrev_b32_e32 v8, 16, v67
	v_and_b32_e32 v9, 0xffff0000, v67
	v_lshlrev_b32_e32 v10, 16, v71
	v_and_b32_e32 v11, 0xffff0000, v71
	s_andn2_b64 vcc, exec, s[4:5]
	s_mov_b64 s[4:5], -1
	flat_store_dwordx4 v[16:17], v[12:15]
	v_pk_fma_f32 v[2:3], v[2:3], v[10:11], v[8:9]
	flat_store_dwordx4 v[16:17], v[4:7] offset:128
	flat_store_dwordx4 v[16:17], v[0:3] offset:144
	s_cbranch_vccnz .LBB0_803
	s_and_b64 vcc, exec, s[0:1]
	s_cbranch_vccnz .LBB0_802
	s_barrier
	s_branch .LBB0_802
